# mix reverse-order group chosen by XCD parity (bit 0 of the block index) instead of bit 3
# speedup vs baseline: 1.0028x; 1.0028x over previous
; #define LAS __attribute__((address_space(3)))
; __device__ __forceinline__ void attn_item(const bf16_t* __restrict__ Q, const bf16_t* __restrict__ Kb, const bf16_t* __restrict__ VT, const bf16_t* __restrict__ GA, ...
;     const int r = lane & 31, hh = lane >> 5;
;     const int rl = lane >> 3, cl = lane & 7;
;     const int tokq = b * SEQ + c * 64 + half * 32;
;     const int qloc = half * 32 + r;
;     const int pr = (r & ~12) | ((r & 4) << 1) | ((r & 8) >> 1);
;     const int jmin = c >= 8 ? 0 : 8 - c;
;     const int tk0 = b * SEQ + (c - 8 + jmin) * 64;
; template <int L> __device__ __forceinline__ void phase_mix(const Args& args, LAS unsigned char* lds) {
;     const int tid = threadIdx.x, lane = tid & 63, wave = __builtin_amdgcn_readfirstlane(tid >> 6);
;     const int G = gridDim.x, blk = blockIdx.x;
;     unsigned char* ws = args.ws;
;     const bf16_t* segb = (const bf16_t*)(ws + WS_SEG);
;     bf16_t* OA = (bf16_t*)(ws + WS_O);
;     constexpr size_t SE = (size_t)MT * DH;
;     LAS float* btab = (LAS float*)(lds + 8 * ATT_WAVE_LDS + wave * 1536);
;     LAS unsigned char* wl = lds + (wave >> 1) * (2 * ATT_WAVE_LDS);
;     int cur_h = -1;
;     for (int u = blk; u < 1024 + 512 + 256; u += G) {
;         if (u < 1024) {
;             const int hg = u & 3, b = (u >> 2) & 7, c = u >> 5;
;             const int h = hg * 4 + (wave >> 1), half = wave & 1;
;             if (h != cur_h) { const float* rb = args.in[3] + (size_t)(L * 16 + h) * NREL;
; #pragma unroll
;                 for (int i = 0; i < 6; ++i) { const int idx = i * 64 + lane; btab[idx] = rb[idx < NREL ? idx : NREL - 1] * LOG2E; }
;                 cur_h = h; }
;             attn_item(segb, segb + SE, (const bf16_t*)(ws + WS_VT), segb + 3 * SE, OA, btab, wl, b, c, h, half, lane);
;         } else if (u < 1536) {
;             conv_unit(segb + 4 * SE, segb + 5 * SE, segb + 6 * SE, segb + 7 * SE, OA + SE, args.in[4] + (size_t)L * 3 * DH, u - 1024, tid);
;         } else {
;             const int su = u - 1536; const int gh = su & 1, n = (su >> 1) & 15, b = su >> 5;
;             sgu_unit((const bf16_t*)(ws + WS_VCT), segb + 8 * SE, segb + 10 * SE, OA + 2 * SE, (const bf16_t*)(ws + WS_SGUW) + (size_t)L * 8 * 16384, args.in[8] + (size_t)L * 8 * 128,
;                      args.in[5] + (size_t)L * DH, args.in[6] + (size_t)L * DH, b, n, gh, lds, tid);
;         }
;     }
; }
.LBB0_214:
	s_cmp_lt_i32 s22, 3
	s_cselect_b64 s[2:3], -1, 0
	s_cmp_gt_i32 s23, 2
	s_cselect_b64 s[4:5], -1, 0
	s_and_b64 s[2:3], s[2:3], s[4:5]
	s_andn2_b64 vcc, exec, s[2:3]
	s_cbranch_vccnz .LBB0_313
	s_load_dword s74, s[0:1], 0x88
	s_waitcnt lgkmcnt(0)
	s_add_u32 s10, s0, 0x88
	s_addc_u32 s11, s1, 0
	s_cmpk_gt_i32 s85, 0x6ff
	v_readfirstlane_b32 s6, v217
	s_cbranch_scc1 .LBB0_263
	s_lshr_b32 s2, s6, 6
	s_add_u32 s24, s20, 0xf200000
	s_addc_u32 s25, s21, 0
	s_add_u32 s26, s20, 0x31200000
	s_addc_u32 s27, s21, 0
	s_mulk_i32 s2, 0x600
	s_lshr_b32 s76, s6, 7
	s_add_i32 s7, s2, 0
	s_mul_i32 s2, s76, 0x9000
	s_add_i32 s75, s7, 0x24000
	s_add_i32 s77, s2, 0
	s_add_u32 s30, s20, 0x1f200000
	s_addc_u32 s31, s21, 0
	s_add_u32 s34, s20, 0x23200000
	s_addc_u32 s35, s21, 0
	s_add_u32 s36, s20, 0x35200000
	s_addc_u32 s37, s21, 0
	s_add_u32 s38, s20, 0x17200000
	s_addc_u32 s39, s21, 0
	s_add_u32 s40, s20, 0x19200000
	s_addc_u32 s41, s21, 0
	s_add_u32 s42, s20, 0x1b200000
	s_addc_u32 s43, s21, 0
	s_add_u32 s44, s20, 0x1d200000
	s_addc_u32 s45, s21, 0
	s_add_u32 s46, s20, 0x33200000
	s_addc_u32 s47, s21, 0
	s_bfe_u32 s8, s6, 0x10006
	s_add_u32 s48, s20, 0x15200000
	s_addc_u32 s49, s21, 0
	s_lshl_b32 s78, s8, 5
	v_and_b32_e32 v3, 3, v217
	s_bitcmp1_b32 s6, 6
	v_lshlrev_b32_e32 v4, 3, v3
	v_lshlrev_b32_e32 v157, 4, v3
	v_lshrrev_b32_e32 v3, 4, v217
	v_mov_b32_e32 v5, 0xffff8000
	v_lshlrev_b32_e32 v6, 1, v217
	v_lshrrev_b32_e32 v7, 1, v217
	s_cselect_b64 s[50:51], -1, 0
	s_add_u32 s52, s20, 0x37400000
	v_bfe_u32 v1, v217, 5, 1
	v_and_or_b32 v161, v3, 56, v5
	v_and_b32_e32 v5, 19, v217
	v_and_b32_e32 v6, 8, v6
	v_and_b32_e32 v8, 4, v7
	s_addc_u32 s53, s21, 0
	s_load_dwordx8 s[12:19], s[0:1], 0x18
	v_and_b32_e32 v131, 31, v217
	v_lshlrev_b32_e32 v154, 3, v217
	v_lshlrev_b32_e32 v130, 3, v1
	v_lshl_add_u32 v158, v1, 6, 0
	v_or3_b32 v5, v6, v5, v8
	s_add_u32 s54, s20, 0x11200000
	s_movk_i32 s6, 0x90
	v_lshlrev_b32_e32 v167, 4, v1
	v_mov_b32_e32 v1, s77
	s_mulk_i32 s8, 0x4800
	v_and_b32_e32 v160, 0x3f8, v154
	s_addc_u32 s55, s21, 0
	v_mul_u32_u24_e32 v166, 0x90, v5
	v_mad_u32_u24 v5, v5, s6, v1
	v_mad_u32_u24 v1, v131, s6, v1
	s_add_i32 s6, s77, s8
	s_load_dwordx2 s[8:9], s[0:1], 0x40
	v_mov_b32_e32 v133, 0
	v_lshlrev_b32_e32 v132, 1, v160
	v_and_b32_e32 v3, 7, v217
	v_lshl_add_u64 v[134:135], s[40:41], 0, v[132:133]
	v_lshl_add_u64 v[136:137], s[42:43], 0, v[132:133]
	v_lshlrev_b32_e32 v138, 3, v3
	v_lshlrev_b32_e32 v3, 4, v3
	v_lshlrev_b32_e32 v132, 2, v160
	s_lshl_b32 s79, s85, 6
	s_lshl_b32 s80, s74, 6
	s_lshl_b32 s81, s85, 2
	s_lshl_b32 s82, s74, 2
	v_add_u32_e32 v6, s6, v130
	v_add_u32_e32 v168, s6, v3
	s_waitcnt lgkmcnt(0)
	v_lshl_add_u64 v[140:141], s[14:15], 0, v[132:133]
	s_mov_b64 s[14:15], 0x1000
	s_add_u32 s6, s20, 0x39600060
	v_lshl_add_u64 v[142:143], v[140:141], 0, s[14:15]
	s_mov_b64 s[14:15], 0x2000
	v_writelane_b32 v244, s6, 2
	s_addc_u32 s6, s21, 0
	v_lshl_add_u64 v[144:145], v[140:141], 0, s[14:15]
	s_add_u32 s14, s8, 0x80
	s_addc_u32 s15, s9, 0
	v_bfe_u32 v162, v217, 3, 3
	v_or_b32_e32 v173, s78, v131
	v_and_b32_e32 v9, 15, v217
	v_writelane_b32 v244, s6, 4
	s_add_u32 s6, s20, 0x39600080
	v_and_b32_e32 v0, 63, v217
	v_bfe_u32 v2, v217, 2, 4
	v_mul_u32_u24_e32 v163, 0x90, v162
	v_or_b32_e32 v169, 8, v162
	v_sub_u32_e32 v8, v173, v130
	v_lshlrev_b32_e32 v132, 4, v9
	v_writelane_b32 v244, s6, 5
	s_addc_u32 s6, s21, 0
	v_cmp_gt_u32_e64 s[2:3], 16, v0
	s_movk_i32 s4, 0x80
	v_mul_u32_u24_e32 v159, 0x50, v2
	v_add3_u32 v164, s77, v3, v163
	v_mul_u32_u24_e32 v165, 0x90, v131
	v_mul_u32_u24_e32 v3, 0x90, v169
	v_lshl_add_u32 v172, v0, 2, s75
	v_lshl_add_u64 v[146:147], s[20:21], 0, v[132:133]
	v_lshlrev_b32_e32 v132, 8, v131
	v_lshl_or_b32 v175, v2, 10, v4
	s_add_u32 s56, s8, 0x180
	v_lshl_add_u32 v2, v8, 2, s7
	v_lshlrev_b32_e32 v178, 2, v0
	v_mbcnt_lo_u32_b32 v0, -1, 0
	s_mov_b32 s29, 0
	v_bfe_u32 v139, v217, 4, 2
	v_and_b32_e32 v155, 0x78, v154
	v_cmp_gt_u32_e64 s[4:5], s4, v217
	v_mul_u32_u24_e32 v156, 0x50, v131
	v_or_b32_e32 v170, 16, v162
	v_or_b32_e32 v171, 24, v162
	v_or_b32_e32 v174, 0x1c00, v154
	v_and_b32_e32 v148, 16, v7
	v_mov_b32_e32 v149, v133
	v_lshl_add_u64 v[150:151], s[20:21], 0, v[132:133]
	s_addc_u32 s57, s9, 0
	v_add_u32_e32 v176, 0x24720, v2
	s_mov_b32 s83, -1
	s_mov_b32 s86, 0x8080
	s_mov_b32 s87, 0x39640000
	s_mov_b32 s88, 0x39660000
	s_mov_b32 s89, 0x39680000
	s_mov_b32 s90, 0x396a0000
	s_mov_b32 s91, 0x396c0000
	s_mov_b32 s92, 0x396e0000
	v_mov_b32_e32 v177, 0x260
	s_mov_b32 s95, 0x37204000
	s_mov_b32 s96, 0x37202000
	s_mov_b64 s[58:59], 0x8000
	s_mov_b64 s[60:61], 0x404000
	s_mov_b64 s[62:63], 0x200
	s_mov_b32 s97, 0x37206000
	s_mov_b32 s93, 0x37200000
	v_add_u32_e32 v179, v1, v167
	s_mov_b32 s94, 0x41000000
	v_add_u32_e32 v180, v6, v165
	v_add_u32_e32 v181, v168, v3
	v_mbcnt_hi_u32_b32 v182, -1, v0
	v_add_u32_e32 v183, v5, v167
	s_mov_b32 s84, s85
	s_cmpk_lg_u32 s74, 0x100
	s_cbranch_scc1 .Lmix0_fwd
	s_bitcmp1_b32 s85, 0
	s_cbranch_scc0 .Lmix0_fwd
	s_addk_i32 s84, 0x600
	s_lshl_b32 s79, s84, 6
	s_lshl_b32 s81, s84, 2
	s_sub_i32 s74, 0, s74
	s_sub_i32 s80, 0, s80
	s_sub_i32 s82, 0, s82

; #define LAS __attribute__((address_space(3)))
; __device__ __forceinline__ void attn_item(const bf16_t* __restrict__ Q, const bf16_t* __restrict__ Kb, const bf16_t* __restrict__ VT, const bf16_t* __restrict__ GA, ...
;     const int r = lane & 31, hh = lane >> 5;
;     const int rl = lane >> 3, cl = lane & 7;
;     const int tokq = b * SEQ + c * 64 + half * 32;
;     const int qloc = half * 32 + r;
;     const int pr = (r & ~12) | ((r & 4) << 1) | ((r & 8) >> 1);
;     const int jmin = c >= 8 ? 0 : 8 - c;
;     const int tk0 = b * SEQ + (c - 8 + jmin) * 64;
; template <int L> __device__ __forceinline__ void phase_mix(const Args& args, LAS unsigned char* lds) {
;     const int tid = threadIdx.x, lane = tid & 63, wave = __builtin_amdgcn_readfirstlane(tid >> 6);
;     const int G = gridDim.x, blk = blockIdx.x;
;     unsigned char* ws = args.ws;
;     const bf16_t* segb = (const bf16_t*)(ws + WS_SEG);
;     bf16_t* OA = (bf16_t*)(ws + WS_O);
;     constexpr size_t SE = (size_t)MT * DH;
;     LAS float* btab = (LAS float*)(lds + 8 * ATT_WAVE_LDS + wave * 1536);
;     LAS unsigned char* wl = lds + (wave >> 1) * (2 * ATT_WAVE_LDS);
;     int cur_h = -1;
;     for (int u = blk; u < 1024 + 512 + 256; u += G) {
;         if (u < 1024) {
;             const int hg = u & 3, b = (u >> 2) & 7, c = u >> 5;
;             const int h = hg * 4 + (wave >> 1), half = wave & 1;
;             if (h != cur_h) { const float* rb = args.in[3] + (size_t)(L * 16 + h) * NREL;
; #pragma unroll
;                 for (int i = 0; i < 6; ++i) { const int idx = i * 64 + lane; btab[idx] = rb[idx < NREL ? idx : NREL - 1] * LOG2E; }
;                 cur_h = h; }
;             attn_item(segb, segb + SE, (const bf16_t*)(ws + WS_VT), segb + 3 * SE, OA, btab, wl, b, c, h, half, lane);
;         } else if (u < 1536) {
;             conv_unit(segb + 4 * SE, segb + 5 * SE, segb + 6 * SE, segb + 7 * SE, OA + SE, args.in[4] + (size_t)L * 3 * DH, u - 1024, tid);
;         } else {
;             const int su = u - 1536; const int gh = su & 1, n = (su >> 1) & 15, b = su >> 5;
;             sgu_unit((const bf16_t*)(ws + WS_VCT), segb + 8 * SE, segb + 10 * SE, OA + 2 * SE, (const bf16_t*)(ws + WS_SGUW) + (size_t)L * 8 * 16384, args.in[8] + (size_t)L * 8 * 128,
;                      args.in[5] + (size_t)L * DH, args.in[6] + (size_t)L * DH, b, n, gh, lds, tid);
;         }
;     }
; }
.LBB0_638:
	s_cmp_lt_i32 s22, 8
	s_cselect_b64 s[2:3], -1, 0
	s_cmp_gt_i32 s23, 7
	s_cselect_b64 s[4:5], -1, 0
	s_and_b64 s[2:3], s[2:3], s[4:5]
	s_andn2_b64 vcc, exec, s[2:3]
	s_cbranch_vccnz .LBB0_737
	s_load_dword s74, s[0:1], 0x88
	s_waitcnt lgkmcnt(0)
	s_add_u32 s10, s0, 0x88
	s_addc_u32 s11, s1, 0
	s_cmpk_gt_i32 s85, 0x6ff
	v_readfirstlane_b32 s6, v217
	s_cbranch_scc1 .LBB0_687
	s_lshr_b32 s2, s6, 6
	s_add_u32 s24, s20, 0xf200000
	s_addc_u32 s25, s21, 0
	s_add_u32 s26, s20, 0x31200000
	s_addc_u32 s27, s21, 0
	s_mulk_i32 s2, 0x600
	s_lshr_b32 s76, s6, 7
	s_add_i32 s7, s2, 0
	s_mul_i32 s2, s76, 0x9000
	s_add_i32 s75, s7, 0x24000
	s_add_i32 s77, s2, 0
	s_add_u32 s30, s20, 0x1f200000
	s_addc_u32 s31, s21, 0
	s_add_u32 s34, s20, 0x23200000
	s_addc_u32 s35, s21, 0
	s_add_u32 s36, s20, 0x35200000
	s_addc_u32 s37, s21, 0
	s_add_u32 s38, s20, 0x17200000
	s_addc_u32 s39, s21, 0
	s_add_u32 s40, s20, 0x19200000
	s_addc_u32 s41, s21, 0
	s_add_u32 s42, s20, 0x1b200000
	s_addc_u32 s43, s21, 0
	s_add_u32 s44, s20, 0x1d200000
	s_addc_u32 s45, s21, 0
	s_add_u32 s46, s20, 0x33200000
	s_addc_u32 s47, s21, 0
	s_bfe_u32 s8, s6, 0x10006
	s_add_u32 s48, s20, 0x15200000
	s_addc_u32 s49, s21, 0
	s_lshl_b32 s78, s8, 5
	v_and_b32_e32 v2, 3, v217
	s_bitcmp1_b32 s6, 6
	s_load_dwordx8 s[12:19], s[0:1], 0x18
	v_lshlrev_b32_e32 v154, 3, v217
	v_lshlrev_b32_e32 v5, 3, v2
	v_lshlrev_b32_e32 v157, 4, v2
	v_lshrrev_b32_e32 v2, 4, v217
	v_mov_b32_e32 v3, 0xffff8000
	v_lshlrev_b32_e32 v6, 1, v217
	v_lshrrev_b32_e32 v7, 1, v217
	s_cselect_b64 s[50:51], -1, 0
	s_add_u32 s52, s20, 0x37400000
	v_bfe_u32 v1, v217, 5, 1
	v_and_b32_e32 v160, 0x3f8, v154
	v_and_or_b32 v161, v2, 56, v3
	v_and_b32_e32 v3, 19, v217
	v_and_b32_e32 v6, 8, v6
	v_and_b32_e32 v8, 4, v7
	s_addc_u32 s53, s21, 0
	v_and_b32_e32 v131, 31, v217
	v_lshlrev_b32_e32 v130, 3, v1
	v_mov_b32_e32 v133, 0
	v_lshl_add_u32 v158, v1, 6, 0
	v_lshlrev_b32_e32 v132, 1, v160
	v_bfe_u32 v162, v217, 3, 3
	v_and_b32_e32 v2, 7, v217
	v_or3_b32 v3, v6, v3, v8
	s_add_u32 s54, s20, 0x11200000
	s_movk_i32 s6, 0x90
	v_lshlrev_b32_e32 v167, 4, v1
	v_mov_b32_e32 v1, s77
	s_mulk_i32 s8, 0x4800
	v_lshl_add_u64 v[134:135], s[40:41], 0, v[132:133]
	v_lshl_add_u64 v[136:137], s[42:43], 0, v[132:133]
	v_lshlrev_b32_e32 v138, 3, v2
	s_addc_u32 s55, s21, 0
	v_mul_u32_u24_e32 v163, 0x90, v162
	v_lshlrev_b32_e32 v2, 4, v2
	v_mad_u32_u24 v6, v3, s6, v1
	v_mad_u32_u24 v1, v131, s6, v1
	s_add_i32 s6, s77, s8
	v_lshlrev_b32_e32 v132, 2, v160
	v_add3_u32 v164, s77, v2, v163
	v_mul_u32_u24_e32 v166, 0x90, v3
	v_add_u32_e32 v168, s6, v2
	s_waitcnt lgkmcnt(0)
	v_lshl_add_u64 v[2:3], s[14:15], 0, v[132:133]
	s_mov_b64 s[14:15], 0x3000
	s_lshl_b32 s79, s85, 6
	s_lshl_b32 s80, s74, 6
	s_lshl_b32 s81, s85, 2
	s_lshl_b32 s82, s74, 2
	v_add_u32_e32 v8, s6, v130
	v_lshl_add_u64 v[140:141], v[2:3], 0, s[14:15]
	s_mov_b64 s[14:15], 0x4000
	s_add_u32 s6, s20, 0x39600060
	s_load_dwordx2 s[8:9], s[0:1], 0x40
	v_lshl_add_u64 v[142:143], v[2:3], 0, s[14:15]
	s_mov_b64 s[14:15], 0x5000
	v_writelane_b32 v244, s6, 2
	s_addc_u32 s6, s21, 0
	v_lshl_add_u64 v[144:145], v[2:3], 0, s[14:15]
	s_add_u32 s14, s18, 0x1000
	s_addc_u32 s15, s19, 0
	s_add_u32 s16, s16, 0x1000
	s_addc_u32 s17, s17, 0
	s_waitcnt lgkmcnt(0)
	s_add_u32 s18, s8, 0x1100
	s_addc_u32 s19, s9, 0
	v_or_b32_e32 v173, s78, v131
	v_and_b32_e32 v2, 15, v217
	v_writelane_b32 v244, s6, 4
	s_add_u32 s6, s20, 0x39600080
	v_and_b32_e32 v0, 63, v217
	v_or_b32_e32 v169, 8, v162
	v_sub_u32_e32 v10, v173, v130
	v_lshlrev_b32_e32 v132, 4, v2
	s_addc_u32 s86, s21, 0
	v_cmp_gt_u32_e64 s[2:3], 16, v0
	s_movk_i32 s4, 0x80
	v_bfe_u32 v4, v217, 2, 4
	v_mul_u32_u24_e32 v165, 0x90, v131
	v_mul_u32_u24_e32 v9, 0x90, v169
	v_lshl_add_u32 v172, v0, 2, s75
	v_lshl_add_u64 v[146:147], s[20:21], 0, v[132:133]
	v_lshlrev_b32_e32 v132, 8, v131
	s_add_u32 s56, s8, 0x1180
	v_lshl_add_u32 v2, v10, 2, s7
	v_lshlrev_b32_e32 v178, 2, v0
	v_mbcnt_lo_u32_b32 v0, -1, 0
	s_mov_b32 s29, 0
	v_bfe_u32 v139, v217, 4, 2
	v_and_b32_e32 v155, 0x78, v154
	v_cmp_gt_u32_e64 s[4:5], s4, v217
	v_mul_u32_u24_e32 v156, 0x50, v131
	v_mul_u32_u24_e32 v159, 0x50, v4
	v_or_b32_e32 v170, 16, v162
	v_or_b32_e32 v171, 24, v162
	v_or_b32_e32 v174, 0x1c00, v154
	v_and_b32_e32 v148, 16, v7
	v_mov_b32_e32 v149, v133
	v_lshl_add_u64 v[150:151], s[20:21], 0, v[132:133]
	v_lshl_or_b32 v175, v4, 10, v5
	v_writelane_b32 v244, s6, 5
	s_addc_u32 s57, s9, 0
	v_add_u32_e32 v176, 0x24720, v2
	s_mov_b32 s83, -1
	s_mov_b32 s87, 0x8080
	s_mov_b32 s88, 0x39640000
	s_mov_b32 s89, 0x39660000
	s_mov_b32 s90, 0x39680000
	s_mov_b32 s91, 0x396a0000
	s_mov_b32 s92, 0x396c0000
	s_mov_b32 s93, 0x396e0000
	v_mov_b32_e32 v177, 0x260
	s_mov_b32 s96, 0x37244000
	s_mov_b32 s97, 0x37242000
	s_mov_b64 s[58:59], 0x8000
	s_mov_b64 s[60:61], 0x404000
	s_mov_b64 s[62:63], 0x200
	s_mov_b32 s94, 0x37246000
	s_mov_b32 s95, 0x37240000
	v_add_u32_e32 v179, v1, v167
	s_mov_b32 s33, 0x41000000
	v_add_u32_e32 v180, v8, v165
	v_add_u32_e32 v181, v168, v9
	v_mbcnt_hi_u32_b32 v182, -1, v0
	v_add_u32_e32 v183, v6, v167
	s_mov_b32 s6, s85
	s_cmpk_lg_u32 s74, 0x100
	s_cbranch_scc1 .Lmix1_fwd
	s_bitcmp1_b32 s85, 0
	s_cbranch_scc0 .Lmix1_fwd
	s_addk_i32 s6, 0x600
	s_lshl_b32 s79, s6, 6
	s_lshl_b32 s81, s6, 2
	s_sub_i32 s74, 0, s74
	s_sub_i32 s80, 0, s80
	s_sub_i32 s82, 0, s82
